# GEMM bf16 epilogue modes 1/2: straight-line path whose two 8-byte stores per lane and row group become one 16-byte store after a v_permlane16_swap pair (64 contiguous bytes per row per store)
# speedup vs baseline: 1.0177x; 1.0177x over previous
; __device__ __forceinline__ unsigned pk2(float lo, float hi) { f32x2c v = {lo, hi}; return __builtin_bit_cast(unsigned, __builtin_convertvector(v, bf16x2c)); }
; __device__ __forceinline__ void epilogue(const f32x4 (&acc)[2][2][4][2], const Unit& u, LAS unsigned char* lds, int wr, int wc, int fr, int fq) {
;     ...
;         bf16_t* C = (bf16_t*)Cp;
; #pragma unroll
;         for (int ai = 0; ai < 2; ++ai)
; #pragma unroll
;             for (int m = 0; m < 4; ++m) { bf16_t* rowp = C + (size_t)(row0 + ai * HALF + m * 16) * ldc + col0;
; #pragma unroll
;                 for (int bj = 0; bj < 2; ++bj)
; #pragma unroll
;                     for (int n = 0; n < 2; ++n) { const f32x4 v = acc[ai][bj][m][n]; u32x2 w;
;                         w.x = pk2(act_fn(v[0], mode), act_fn(v[1], mode)); w.y = pk2(act_fn(v[2], mode), act_fn(v[3], mode));
;                         *(u32x2*)(rowp + bj * HALF + n * 16) = w; } }
.Lepi_m1:
	v_ashrrev_i32_e32 v141, 31, v140
	v_lshl_add_u64 v[142:143], v[140:141], 1, s[8:9]
	v_ashrrev_i32_e32 v141, 31, v161
	v_mul_lo_u32 v165, s27, v161
	v_mul_lo_u32 v141, s26, v141
	v_mad_u64_u32 v[144:145], vcc, s26, v161, 0
	v_add3_u32 v145, v145, v141, v165
	v_lshl_add_u64 v[144:145], v[144:145], 1, v[142:143]
	v_mbcnt_lo_u32_b32 v248, -1, 0
	v_mbcnt_hi_u32_b32 v248, -1, v248
	v_and_b32_e32 v248, 16, v248
	v_lshrrev_b32_e32 v249, 1, v248
	v_add_u32_e32 v248, v248, v249
	v_add_co_u32_e32 v144, vcc, v248, v144
	s_nop 1
	v_addc_co_u32_e32 v145, vcc, 0, v145, vcc
	s_lshl_b64 s[2:3], s[26:27], 5
	v_cvt_pk_bf16_f32 v240, v128, v129
	v_cvt_pk_bf16_f32 v241, v130, v131
	v_cvt_pk_bf16_f32 v242, v124, v125
	v_cvt_pk_bf16_f32 v243, v126, v127
	s_nop 1
	v_permlane16_swap_b32 v240, v242
	v_permlane16_swap_b32 v241, v243
	global_store_dwordx4 v[144:145], v[240:243], off
	v_cvt_pk_bf16_f32 v244, v120, v121
	v_cvt_pk_bf16_f32 v245, v122, v123
	v_cvt_pk_bf16_f32 v246, v116, v117
	v_cvt_pk_bf16_f32 v247, v118, v119
	s_nop 1
	v_permlane16_swap_b32 v244, v246
	v_permlane16_swap_b32 v245, v247
	global_store_dwordx4 v[144:145], v[244:247], off offset:256
	v_lshl_add_u64 v[144:145], s[2:3], 0, v[144:145]
	v_cvt_pk_bf16_f32 v240, v112, v113
	v_cvt_pk_bf16_f32 v241, v114, v115
	v_cvt_pk_bf16_f32 v242, v108, v109
	v_cvt_pk_bf16_f32 v243, v110, v111
	s_nop 1
	v_permlane16_swap_b32 v240, v242
	v_permlane16_swap_b32 v241, v243
	global_store_dwordx4 v[144:145], v[240:243], off
	v_cvt_pk_bf16_f32 v244, v104, v105
	v_cvt_pk_bf16_f32 v245, v106, v107
	v_cvt_pk_bf16_f32 v246, v100, v101
	v_cvt_pk_bf16_f32 v247, v102, v103
	s_nop 1
	v_permlane16_swap_b32 v244, v246
	v_permlane16_swap_b32 v245, v247
	global_store_dwordx4 v[144:145], v[244:247], off offset:256
	v_lshl_add_u64 v[144:145], s[2:3], 0, v[144:145]
	v_cvt_pk_bf16_f32 v240, v96, v97
	v_cvt_pk_bf16_f32 v241, v98, v99
	v_cvt_pk_bf16_f32 v242, v92, v93
	v_cvt_pk_bf16_f32 v243, v94, v95
	s_nop 1
	v_permlane16_swap_b32 v240, v242
	v_permlane16_swap_b32 v241, v243
	global_store_dwordx4 v[144:145], v[240:243], off
	v_cvt_pk_bf16_f32 v244, v88, v89
	v_cvt_pk_bf16_f32 v245, v90, v91
	v_cvt_pk_bf16_f32 v246, v84, v85
	v_cvt_pk_bf16_f32 v247, v86, v87
	s_nop 1
	v_permlane16_swap_b32 v244, v246
	v_permlane16_swap_b32 v245, v247
	global_store_dwordx4 v[144:145], v[244:247], off offset:256
	v_lshl_add_u64 v[144:145], s[2:3], 0, v[144:145]
	v_cvt_pk_bf16_f32 v240, v80, v81
	v_cvt_pk_bf16_f32 v241, v82, v83
	v_cvt_pk_bf16_f32 v242, v76, v77
	v_cvt_pk_bf16_f32 v243, v78, v79
	s_nop 1
	v_permlane16_swap_b32 v240, v242
	v_permlane16_swap_b32 v241, v243
	global_store_dwordx4 v[144:145], v[240:243], off
	v_cvt_pk_bf16_f32 v244, v72, v73
	v_cvt_pk_bf16_f32 v245, v74, v75
	v_cvt_pk_bf16_f32 v246, v68, v69
	v_cvt_pk_bf16_f32 v247, v70, v71
	s_nop 1
	v_permlane16_swap_b32 v244, v246
	v_permlane16_swap_b32 v245, v247
	global_store_dwordx4 v[144:145], v[244:247], off offset:256
	v_lshl_add_u64 v[144:145], s[2:3], 2, v[144:145]
	v_lshl_add_u64 v[144:145], s[2:3], 0, v[144:145]
	v_cvt_pk_bf16_f32 v240, v64, v65
	v_cvt_pk_bf16_f32 v241, v66, v67
	v_cvt_pk_bf16_f32 v242, v60, v61
	v_cvt_pk_bf16_f32 v243, v62, v63
	s_nop 1
	v_permlane16_swap_b32 v240, v242
	v_permlane16_swap_b32 v241, v243
	global_store_dwordx4 v[144:145], v[240:243], off
	v_cvt_pk_bf16_f32 v244, v56, v57
	v_cvt_pk_bf16_f32 v245, v58, v59
	v_cvt_pk_bf16_f32 v246, v52, v53
	v_cvt_pk_bf16_f32 v247, v54, v55
	s_nop 1
	v_permlane16_swap_b32 v244, v246
	v_permlane16_swap_b32 v245, v247
	global_store_dwordx4 v[144:145], v[244:247], off offset:256
	v_lshl_add_u64 v[144:145], s[2:3], 0, v[144:145]
	v_cvt_pk_bf16_f32 v240, v48, v49
	v_cvt_pk_bf16_f32 v241, v50, v51
	v_cvt_pk_bf16_f32 v242, v44, v45
	v_cvt_pk_bf16_f32 v243, v46, v47
	s_nop 1
	v_permlane16_swap_b32 v240, v242
	v_permlane16_swap_b32 v241, v243
	global_store_dwordx4 v[144:145], v[240:243], off
	v_cvt_pk_bf16_f32 v244, v40, v41
	v_cvt_pk_bf16_f32 v245, v42, v43
	v_cvt_pk_bf16_f32 v246, v36, v37
	v_cvt_pk_bf16_f32 v247, v38, v39
	s_nop 1
	v_permlane16_swap_b32 v244, v246
	v_permlane16_swap_b32 v245, v247
	global_store_dwordx4 v[144:145], v[244:247], off offset:256
	v_lshl_add_u64 v[144:145], s[2:3], 0, v[144:145]
	v_cvt_pk_bf16_f32 v240, v32, v33
	v_cvt_pk_bf16_f32 v241, v34, v35
	v_cvt_pk_bf16_f32 v242, v28, v29
	v_cvt_pk_bf16_f32 v243, v30, v31
	s_nop 1
	v_permlane16_swap_b32 v240, v242
	v_permlane16_swap_b32 v241, v243
	global_store_dwordx4 v[144:145], v[240:243], off
	v_cvt_pk_bf16_f32 v244, v24, v25
	v_cvt_pk_bf16_f32 v245, v26, v27
	v_cvt_pk_bf16_f32 v246, v20, v21
	v_cvt_pk_bf16_f32 v247, v22, v23
	s_nop 1
	v_permlane16_swap_b32 v244, v246
	v_permlane16_swap_b32 v245, v247
	global_store_dwordx4 v[144:145], v[244:247], off offset:256
	v_lshl_add_u64 v[144:145], s[2:3], 0, v[144:145]
	v_cvt_pk_bf16_f32 v240, v16, v17
	v_cvt_pk_bf16_f32 v241, v18, v19
	v_cvt_pk_bf16_f32 v242, v12, v13
	v_cvt_pk_bf16_f32 v243, v14, v15
	s_nop 1
	v_permlane16_swap_b32 v240, v242
	v_permlane16_swap_b32 v241, v243
	global_store_dwordx4 v[144:145], v[240:243], off
	v_cvt_pk_bf16_f32 v244, v8, v9
	v_cvt_pk_bf16_f32 v245, v10, v11
	v_cvt_pk_bf16_f32 v246, v4, v5
	v_cvt_pk_bf16_f32 v247, v6, v7
	s_nop 1
	v_permlane16_swap_b32 v244, v246
	v_permlane16_swap_b32 v245, v247
	global_store_dwordx4 v[144:145], v[244:247], off offset:256
	s_branch .LBB0_1310
; __device__ __forceinline__ unsigned pk2(float lo, float hi) { f32x2c v = {lo, hi}; return __builtin_bit_cast(unsigned, __builtin_convertvector(v, bf16x2c)); }
; __device__ __forceinline__ float act_fn(float v, int mode) {
;     if (mode == 2) { v = fmaxf(v, 0.f); return v * v; }
; __device__ __forceinline__ void epilogue(const f32x4 (&acc)[2][2][4][2], const Unit& u, LAS unsigned char* lds, int wr, int wc, int fr, int fq) {
;     ...
;         bf16_t* C = (bf16_t*)Cp;
; #pragma unroll
;         for (int ai = 0; ai < 2; ++ai)
; #pragma unroll
;             for (int m = 0; m < 4; ++m) { bf16_t* rowp = C + (size_t)(row0 + ai * HALF + m * 16) * ldc + col0;
; #pragma unroll
;                 for (int bj = 0; bj < 2; ++bj)
; #pragma unroll
;                     for (int n = 0; n < 2; ++n) { const f32x4 v = acc[ai][bj][m][n]; u32x2 w;
;                         w.x = pk2(act_fn(v[0], mode), act_fn(v[1], mode)); w.y = pk2(act_fn(v[2], mode), act_fn(v[3], mode));
;                         *(u32x2*)(rowp + bj * HALF + n * 16) = w; } }
.Lepi_m2:
	v_ashrrev_i32_e32 v141, 31, v140
	v_lshl_add_u64 v[142:143], v[140:141], 1, s[8:9]
	v_ashrrev_i32_e32 v141, 31, v161
	v_mul_lo_u32 v165, s27, v161
	v_mul_lo_u32 v141, s26, v141
	v_mad_u64_u32 v[144:145], vcc, s26, v161, 0
	v_add3_u32 v145, v145, v141, v165
	v_lshl_add_u64 v[144:145], v[144:145], 1, v[142:143]
	v_mbcnt_lo_u32_b32 v248, -1, 0
	v_mbcnt_hi_u32_b32 v248, -1, v248
	v_and_b32_e32 v248, 16, v248
	v_lshrrev_b32_e32 v249, 1, v248
	v_add_u32_e32 v248, v248, v249
	v_add_co_u32_e32 v144, vcc, v248, v144
	s_nop 1
	v_addc_co_u32_e32 v145, vcc, 0, v145, vcc
	s_lshl_b64 s[2:3], s[26:27], 5
	v_max_f32_e32 v248, v128, v128
	v_max_f32_e32 v249, v129, v129
	v_max_f32_e32 v250, v130, v130
	v_max_f32_e32 v251, v131, v131
	v_max_f32_e32 v248, 0, v248
	v_max_f32_e32 v249, 0, v249
	v_max_f32_e32 v250, 0, v250
	v_max_f32_e32 v251, 0, v251
	v_mul_f32_e32 v248, v248, v248
	v_mul_f32_e32 v249, v249, v249
	v_mul_f32_e32 v250, v250, v250
	v_mul_f32_e32 v251, v251, v251
	v_cvt_pk_bf16_f32 v240, v248, v249
	v_cvt_pk_bf16_f32 v241, v250, v251
	v_max_f32_e32 v248, v124, v124
	v_max_f32_e32 v249, v125, v125
	v_max_f32_e32 v250, v126, v126
	v_max_f32_e32 v251, v127, v127
	v_max_f32_e32 v248, 0, v248
	v_max_f32_e32 v249, 0, v249
	v_max_f32_e32 v250, 0, v250
	v_max_f32_e32 v251, 0, v251
	v_mul_f32_e32 v248, v248, v248
	v_mul_f32_e32 v249, v249, v249
	v_mul_f32_e32 v250, v250, v250
	v_mul_f32_e32 v251, v251, v251
	v_cvt_pk_bf16_f32 v242, v248, v249
	v_cvt_pk_bf16_f32 v243, v250, v251
	s_nop 1
	v_permlane16_swap_b32 v240, v242
	v_permlane16_swap_b32 v241, v243
	global_store_dwordx4 v[144:145], v[240:243], off
	v_max_f32_e32 v248, v120, v120
	v_max_f32_e32 v249, v121, v121
	v_max_f32_e32 v250, v122, v122
	v_max_f32_e32 v251, v123, v123
	v_max_f32_e32 v248, 0, v248
	v_max_f32_e32 v249, 0, v249
	v_max_f32_e32 v250, 0, v250
	v_max_f32_e32 v251, 0, v251
	v_mul_f32_e32 v248, v248, v248
	v_mul_f32_e32 v249, v249, v249
	v_mul_f32_e32 v250, v250, v250
	v_mul_f32_e32 v251, v251, v251
	v_cvt_pk_bf16_f32 v244, v248, v249
	v_cvt_pk_bf16_f32 v245, v250, v251
	v_max_f32_e32 v248, v116, v116
	v_max_f32_e32 v249, v117, v117
	v_max_f32_e32 v250, v118, v118
	v_max_f32_e32 v251, v119, v119
	v_max_f32_e32 v248, 0, v248
	v_max_f32_e32 v249, 0, v249
	v_max_f32_e32 v250, 0, v250
	v_max_f32_e32 v251, 0, v251
	v_mul_f32_e32 v248, v248, v248
	v_mul_f32_e32 v249, v249, v249
	v_mul_f32_e32 v250, v250, v250
	v_mul_f32_e32 v251, v251, v251
	v_cvt_pk_bf16_f32 v246, v248, v249
	v_cvt_pk_bf16_f32 v247, v250, v251
	s_nop 1
	v_permlane16_swap_b32 v244, v246
	v_permlane16_swap_b32 v245, v247
	global_store_dwordx4 v[144:145], v[244:247], off offset:256
	v_lshl_add_u64 v[144:145], s[2:3], 0, v[144:145]
	v_max_f32_e32 v248, v112, v112
	v_max_f32_e32 v249, v113, v113
	v_max_f32_e32 v250, v114, v114
	v_max_f32_e32 v251, v115, v115
	v_max_f32_e32 v248, 0, v248
	v_max_f32_e32 v249, 0, v249
	v_max_f32_e32 v250, 0, v250
	v_max_f32_e32 v251, 0, v251
	v_mul_f32_e32 v248, v248, v248
	v_mul_f32_e32 v249, v249, v249
	v_mul_f32_e32 v250, v250, v250
	v_mul_f32_e32 v251, v251, v251
	v_cvt_pk_bf16_f32 v240, v248, v249
	v_cvt_pk_bf16_f32 v241, v250, v251
	v_max_f32_e32 v248, v108, v108
	v_max_f32_e32 v249, v109, v109
	v_max_f32_e32 v250, v110, v110
	v_max_f32_e32 v251, v111, v111
	v_max_f32_e32 v248, 0, v248
	v_max_f32_e32 v249, 0, v249
	v_max_f32_e32 v250, 0, v250
	v_max_f32_e32 v251, 0, v251
	v_mul_f32_e32 v248, v248, v248
	v_mul_f32_e32 v249, v249, v249
	v_mul_f32_e32 v250, v250, v250
	v_mul_f32_e32 v251, v251, v251
	v_cvt_pk_bf16_f32 v242, v248, v249
	v_cvt_pk_bf16_f32 v243, v250, v251
	s_nop 1
	v_permlane16_swap_b32 v240, v242
	v_permlane16_swap_b32 v241, v243
	global_store_dwordx4 v[144:145], v[240:243], off
	v_max_f32_e32 v248, v104, v104
	v_max_f32_e32 v249, v105, v105
	v_max_f32_e32 v250, v106, v106
	v_max_f32_e32 v251, v107, v107
	v_max_f32_e32 v248, 0, v248
	v_max_f32_e32 v249, 0, v249
	v_max_f32_e32 v250, 0, v250
	v_max_f32_e32 v251, 0, v251
	v_mul_f32_e32 v248, v248, v248
	v_mul_f32_e32 v249, v249, v249
	v_mul_f32_e32 v250, v250, v250
	v_mul_f32_e32 v251, v251, v251
	v_cvt_pk_bf16_f32 v244, v248, v249
	v_cvt_pk_bf16_f32 v245, v250, v251
	v_max_f32_e32 v248, v100, v100
	v_max_f32_e32 v249, v101, v101
	v_max_f32_e32 v250, v102, v102
	v_max_f32_e32 v251, v103, v103
	v_max_f32_e32 v248, 0, v248
	v_max_f32_e32 v249, 0, v249
	v_max_f32_e32 v250, 0, v250
	v_max_f32_e32 v251, 0, v251
	v_mul_f32_e32 v248, v248, v248
	v_mul_f32_e32 v249, v249, v249
	v_mul_f32_e32 v250, v250, v250
	v_mul_f32_e32 v251, v251, v251
	v_cvt_pk_bf16_f32 v246, v248, v249
	v_cvt_pk_bf16_f32 v247, v250, v251
	s_nop 1
	v_permlane16_swap_b32 v244, v246
	v_permlane16_swap_b32 v245, v247
	global_store_dwordx4 v[144:145], v[244:247], off offset:256
	v_lshl_add_u64 v[144:145], s[2:3], 0, v[144:145]
	v_max_f32_e32 v248, v96, v96
	v_max_f32_e32 v249, v97, v97
	v_max_f32_e32 v250, v98, v98
	v_max_f32_e32 v251, v99, v99
	v_max_f32_e32 v248, 0, v248
	v_max_f32_e32 v249, 0, v249
	v_max_f32_e32 v250, 0, v250
	v_max_f32_e32 v251, 0, v251
	v_mul_f32_e32 v248, v248, v248
	v_mul_f32_e32 v249, v249, v249
	v_mul_f32_e32 v250, v250, v250
	v_mul_f32_e32 v251, v251, v251
	v_cvt_pk_bf16_f32 v240, v248, v249
	v_cvt_pk_bf16_f32 v241, v250, v251
	v_max_f32_e32 v248, v92, v92
	v_max_f32_e32 v249, v93, v93
	v_max_f32_e32 v250, v94, v94
	v_max_f32_e32 v251, v95, v95
	v_max_f32_e32 v248, 0, v248
	v_max_f32_e32 v249, 0, v249
	v_max_f32_e32 v250, 0, v250
	v_max_f32_e32 v251, 0, v251
	v_mul_f32_e32 v248, v248, v248
	v_mul_f32_e32 v249, v249, v249
	v_mul_f32_e32 v250, v250, v250
	v_mul_f32_e32 v251, v251, v251
	v_cvt_pk_bf16_f32 v242, v248, v249
; __device__ __forceinline__ unsigned pk2(float lo, float hi) { f32x2c v = {lo, hi}; return __builtin_bit_cast(unsigned, __builtin_convertvector(v, bf16x2c)); }
; __device__ __forceinline__ float act_fn(float v, int mode) {
;     if (mode == 2) { v = fmaxf(v, 0.f); return v * v; }
; __device__ __forceinline__ void epilogue(const f32x4 (&acc)[2][2][4][2], const Unit& u, LAS unsigned char* lds, int wr, int wc, int fr, int fq) {
;     ...
;         bf16_t* C = (bf16_t*)Cp;
; #pragma unroll
;         for (int ai = 0; ai < 2; ++ai)
; #pragma unroll
;             for (int m = 0; m < 4; ++m) { bf16_t* rowp = C + (size_t)(row0 + ai * HALF + m * 16) * ldc + col0;
; #pragma unroll
;                 for (int bj = 0; bj < 2; ++bj)
; #pragma unroll
;                     for (int n = 0; n < 2; ++n) { const f32x4 v = acc[ai][bj][m][n]; u32x2 w;
;                         w.x = pk2(act_fn(v[0], mode), act_fn(v[1], mode)); w.y = pk2(act_fn(v[2], mode), act_fn(v[3], mode));
;                         *(u32x2*)(rowp + bj * HALF + n * 16) = w; } }
	v_cvt_pk_bf16_f32 v243, v250, v251
	s_nop 1
	v_permlane16_swap_b32 v240, v242
	v_permlane16_swap_b32 v241, v243
	global_store_dwordx4 v[144:145], v[240:243], off
	v_max_f32_e32 v248, v88, v88
	v_max_f32_e32 v249, v89, v89
	v_max_f32_e32 v250, v90, v90
	v_max_f32_e32 v251, v91, v91
	v_max_f32_e32 v248, 0, v248
	v_max_f32_e32 v249, 0, v249
	v_max_f32_e32 v250, 0, v250
	v_max_f32_e32 v251, 0, v251
	v_mul_f32_e32 v248, v248, v248
	v_mul_f32_e32 v249, v249, v249
	v_mul_f32_e32 v250, v250, v250
	v_mul_f32_e32 v251, v251, v251
	v_cvt_pk_bf16_f32 v244, v248, v249
	v_cvt_pk_bf16_f32 v245, v250, v251
	v_max_f32_e32 v248, v84, v84
	v_max_f32_e32 v249, v85, v85
	v_max_f32_e32 v250, v86, v86
	v_max_f32_e32 v251, v87, v87
	v_max_f32_e32 v248, 0, v248
	v_max_f32_e32 v249, 0, v249
	v_max_f32_e32 v250, 0, v250
	v_max_f32_e32 v251, 0, v251
	v_mul_f32_e32 v248, v248, v248
	v_mul_f32_e32 v249, v249, v249
	v_mul_f32_e32 v250, v250, v250
	v_mul_f32_e32 v251, v251, v251
	v_cvt_pk_bf16_f32 v246, v248, v249
	v_cvt_pk_bf16_f32 v247, v250, v251
	s_nop 1
	v_permlane16_swap_b32 v244, v246
	v_permlane16_swap_b32 v245, v247
	global_store_dwordx4 v[144:145], v[244:247], off offset:256
	v_lshl_add_u64 v[144:145], s[2:3], 0, v[144:145]
	v_max_f32_e32 v248, v80, v80
	v_max_f32_e32 v249, v81, v81
	v_max_f32_e32 v250, v82, v82
	v_max_f32_e32 v251, v83, v83
	v_max_f32_e32 v248, 0, v248
	v_max_f32_e32 v249, 0, v249
	v_max_f32_e32 v250, 0, v250
	v_max_f32_e32 v251, 0, v251
	v_mul_f32_e32 v248, v248, v248
	v_mul_f32_e32 v249, v249, v249
	v_mul_f32_e32 v250, v250, v250
	v_mul_f32_e32 v251, v251, v251
	v_cvt_pk_bf16_f32 v240, v248, v249
	v_cvt_pk_bf16_f32 v241, v250, v251
	v_max_f32_e32 v248, v76, v76
	v_max_f32_e32 v249, v77, v77
	v_max_f32_e32 v250, v78, v78
	v_max_f32_e32 v251, v79, v79
	v_max_f32_e32 v248, 0, v248
	v_max_f32_e32 v249, 0, v249
	v_max_f32_e32 v250, 0, v250
	v_max_f32_e32 v251, 0, v251
	v_mul_f32_e32 v248, v248, v248
	v_mul_f32_e32 v249, v249, v249
	v_mul_f32_e32 v250, v250, v250
	v_mul_f32_e32 v251, v251, v251
	v_cvt_pk_bf16_f32 v242, v248, v249
	v_cvt_pk_bf16_f32 v243, v250, v251
	s_nop 1
	v_permlane16_swap_b32 v240, v242
	v_permlane16_swap_b32 v241, v243
	global_store_dwordx4 v[144:145], v[240:243], off
	v_max_f32_e32 v248, v72, v72
	v_max_f32_e32 v249, v73, v73
	v_max_f32_e32 v250, v74, v74
	v_max_f32_e32 v251, v75, v75
	v_max_f32_e32 v248, 0, v248
	v_max_f32_e32 v249, 0, v249
	v_max_f32_e32 v250, 0, v250
	v_max_f32_e32 v251, 0, v251
	v_mul_f32_e32 v248, v248, v248
	v_mul_f32_e32 v249, v249, v249
	v_mul_f32_e32 v250, v250, v250
	v_mul_f32_e32 v251, v251, v251
	v_cvt_pk_bf16_f32 v244, v248, v249
	v_cvt_pk_bf16_f32 v245, v250, v251
	v_max_f32_e32 v248, v68, v68
	v_max_f32_e32 v249, v69, v69
	v_max_f32_e32 v250, v70, v70
	v_max_f32_e32 v251, v71, v71
	v_max_f32_e32 v248, 0, v248
	v_max_f32_e32 v249, 0, v249
	v_max_f32_e32 v250, 0, v250
	v_max_f32_e32 v251, 0, v251
	v_mul_f32_e32 v248, v248, v248
	v_mul_f32_e32 v249, v249, v249
	v_mul_f32_e32 v250, v250, v250
	v_mul_f32_e32 v251, v251, v251
	v_cvt_pk_bf16_f32 v246, v248, v249
	v_cvt_pk_bf16_f32 v247, v250, v251
	s_nop 1
	v_permlane16_swap_b32 v244, v246
	v_permlane16_swap_b32 v245, v247
	global_store_dwordx4 v[144:145], v[244:247], off offset:256
	v_lshl_add_u64 v[144:145], s[2:3], 2, v[144:145]
	v_lshl_add_u64 v[144:145], s[2:3], 0, v[144:145]
	v_max_f32_e32 v248, v64, v64
	v_max_f32_e32 v249, v65, v65
	v_max_f32_e32 v250, v66, v66
	v_max_f32_e32 v251, v67, v67
	v_max_f32_e32 v248, 0, v248
	v_max_f32_e32 v249, 0, v249
	v_max_f32_e32 v250, 0, v250
	v_max_f32_e32 v251, 0, v251
	v_mul_f32_e32 v248, v248, v248
	v_mul_f32_e32 v249, v249, v249
	v_mul_f32_e32 v250, v250, v250
	v_mul_f32_e32 v251, v251, v251
	v_cvt_pk_bf16_f32 v240, v248, v249
	v_cvt_pk_bf16_f32 v241, v250, v251
	v_max_f32_e32 v248, v60, v60
	v_max_f32_e32 v249, v61, v61
	v_max_f32_e32 v250, v62, v62
	v_max_f32_e32 v251, v63, v63
	v_max_f32_e32 v248, 0, v248
	v_max_f32_e32 v249, 0, v249
	v_max_f32_e32 v250, 0, v250
	v_max_f32_e32 v251, 0, v251
	v_mul_f32_e32 v248, v248, v248
	v_mul_f32_e32 v249, v249, v249
	v_mul_f32_e32 v250, v250, v250
	v_mul_f32_e32 v251, v251, v251
	v_cvt_pk_bf16_f32 v242, v248, v249
	v_cvt_pk_bf16_f32 v243, v250, v251
	s_nop 1
	v_permlane16_swap_b32 v240, v242
	v_permlane16_swap_b32 v241, v243
	global_store_dwordx4 v[144:145], v[240:243], off
	v_max_f32_e32 v248, v56, v56
	v_max_f32_e32 v249, v57, v57
	v_max_f32_e32 v250, v58, v58
	v_max_f32_e32 v251, v59, v59
	v_max_f32_e32 v248, 0, v248
	v_max_f32_e32 v249, 0, v249
	v_max_f32_e32 v250, 0, v250
	v_max_f32_e32 v251, 0, v251
	v_mul_f32_e32 v248, v248, v248
	v_mul_f32_e32 v249, v249, v249
	v_mul_f32_e32 v250, v250, v250
	v_mul_f32_e32 v251, v251, v251
	v_cvt_pk_bf16_f32 v244, v248, v249
	v_cvt_pk_bf16_f32 v245, v250, v251
	v_max_f32_e32 v248, v52, v52
	v_max_f32_e32 v249, v53, v53
	v_max_f32_e32 v250, v54, v54
	v_max_f32_e32 v251, v55, v55
	v_max_f32_e32 v248, 0, v248
	v_max_f32_e32 v249, 0, v249
	v_max_f32_e32 v250, 0, v250
	v_max_f32_e32 v251, 0, v251
	v_mul_f32_e32 v248, v248, v248
	v_mul_f32_e32 v249, v249, v249
	v_mul_f32_e32 v250, v250, v250
	v_mul_f32_e32 v251, v251, v251
	v_cvt_pk_bf16_f32 v246, v248, v249
	v_cvt_pk_bf16_f32 v247, v250, v251
	s_nop 1
	v_permlane16_swap_b32 v244, v246
	v_permlane16_swap_b32 v245, v247
	global_store_dwordx4 v[144:145], v[244:247], off offset:256
	v_lshl_add_u64 v[144:145], s[2:3], 0, v[144:145]
	v_max_f32_e32 v248, v48, v48
	v_max_f32_e32 v249, v49, v49
	v_max_f32_e32 v250, v50, v50
	v_max_f32_e32 v251, v51, v51
	v_max_f32_e32 v248, 0, v248
	v_max_f32_e32 v249, 0, v249
	v_max_f32_e32 v250, 0, v250
	v_max_f32_e32 v251, 0, v251
; __device__ __forceinline__ unsigned pk2(float lo, float hi) { f32x2c v = {lo, hi}; return __builtin_bit_cast(unsigned, __builtin_convertvector(v, bf16x2c)); }
; __device__ __forceinline__ float act_fn(float v, int mode) {
;     if (mode == 2) { v = fmaxf(v, 0.f); return v * v; }
; __device__ __forceinline__ void epilogue(const f32x4 (&acc)[2][2][4][2], const Unit& u, LAS unsigned char* lds, int wr, int wc, int fr, int fq) {
;     ...
;         bf16_t* C = (bf16_t*)Cp;
; #pragma unroll
;         for (int ai = 0; ai < 2; ++ai)
; #pragma unroll
;             for (int m = 0; m < 4; ++m) { bf16_t* rowp = C + (size_t)(row0 + ai * HALF + m * 16) * ldc + col0;
; #pragma unroll
;                 for (int bj = 0; bj < 2; ++bj)
; #pragma unroll
;                     for (int n = 0; n < 2; ++n) { const f32x4 v = acc[ai][bj][m][n]; u32x2 w;
;                         w.x = pk2(act_fn(v[0], mode), act_fn(v[1], mode)); w.y = pk2(act_fn(v[2], mode), act_fn(v[3], mode));
;                         *(u32x2*)(rowp + bj * HALF + n * 16) = w; } }
	v_mul_f32_e32 v248, v248, v248
	v_mul_f32_e32 v249, v249, v249
	v_mul_f32_e32 v250, v250, v250
	v_mul_f32_e32 v251, v251, v251
	v_cvt_pk_bf16_f32 v240, v248, v249
	v_cvt_pk_bf16_f32 v241, v250, v251
	v_max_f32_e32 v248, v44, v44
	v_max_f32_e32 v249, v45, v45
	v_max_f32_e32 v250, v46, v46
	v_max_f32_e32 v251, v47, v47
	v_max_f32_e32 v248, 0, v248
	v_max_f32_e32 v249, 0, v249
	v_max_f32_e32 v250, 0, v250
	v_max_f32_e32 v251, 0, v251
	v_mul_f32_e32 v248, v248, v248
	v_mul_f32_e32 v249, v249, v249
	v_mul_f32_e32 v250, v250, v250
	v_mul_f32_e32 v251, v251, v251
	v_cvt_pk_bf16_f32 v242, v248, v249
	v_cvt_pk_bf16_f32 v243, v250, v251
	s_nop 1
	v_permlane16_swap_b32 v240, v242
	v_permlane16_swap_b32 v241, v243
	global_store_dwordx4 v[144:145], v[240:243], off
	v_max_f32_e32 v248, v40, v40
	v_max_f32_e32 v249, v41, v41
	v_max_f32_e32 v250, v42, v42
	v_max_f32_e32 v251, v43, v43
	v_max_f32_e32 v248, 0, v248
	v_max_f32_e32 v249, 0, v249
	v_max_f32_e32 v250, 0, v250
	v_max_f32_e32 v251, 0, v251
	v_mul_f32_e32 v248, v248, v248
	v_mul_f32_e32 v249, v249, v249
	v_mul_f32_e32 v250, v250, v250
	v_mul_f32_e32 v251, v251, v251
	v_cvt_pk_bf16_f32 v244, v248, v249
	v_cvt_pk_bf16_f32 v245, v250, v251
	v_max_f32_e32 v248, v36, v36
	v_max_f32_e32 v249, v37, v37
	v_max_f32_e32 v250, v38, v38
	v_max_f32_e32 v251, v39, v39
	v_max_f32_e32 v248, 0, v248
	v_max_f32_e32 v249, 0, v249
	v_max_f32_e32 v250, 0, v250
	v_max_f32_e32 v251, 0, v251
	v_mul_f32_e32 v248, v248, v248
	v_mul_f32_e32 v249, v249, v249
	v_mul_f32_e32 v250, v250, v250
	v_mul_f32_e32 v251, v251, v251
	v_cvt_pk_bf16_f32 v246, v248, v249
	v_cvt_pk_bf16_f32 v247, v250, v251
	s_nop 1
	v_permlane16_swap_b32 v244, v246
	v_permlane16_swap_b32 v245, v247
	global_store_dwordx4 v[144:145], v[244:247], off offset:256
	v_lshl_add_u64 v[144:145], s[2:3], 0, v[144:145]
	v_max_f32_e32 v248, v32, v32
	v_max_f32_e32 v249, v33, v33
	v_max_f32_e32 v250, v34, v34
	v_max_f32_e32 v251, v35, v35
	v_max_f32_e32 v248, 0, v248
	v_max_f32_e32 v249, 0, v249
	v_max_f32_e32 v250, 0, v250
	v_max_f32_e32 v251, 0, v251
	v_mul_f32_e32 v248, v248, v248
	v_mul_f32_e32 v249, v249, v249
	v_mul_f32_e32 v250, v250, v250
	v_mul_f32_e32 v251, v251, v251
	v_cvt_pk_bf16_f32 v240, v248, v249
	v_cvt_pk_bf16_f32 v241, v250, v251
	v_max_f32_e32 v248, v28, v28
	v_max_f32_e32 v249, v29, v29
	v_max_f32_e32 v250, v30, v30
	v_max_f32_e32 v251, v31, v31
	v_max_f32_e32 v248, 0, v248
	v_max_f32_e32 v249, 0, v249
	v_max_f32_e32 v250, 0, v250
	v_max_f32_e32 v251, 0, v251
	v_mul_f32_e32 v248, v248, v248
	v_mul_f32_e32 v249, v249, v249
	v_mul_f32_e32 v250, v250, v250
	v_mul_f32_e32 v251, v251, v251
	v_cvt_pk_bf16_f32 v242, v248, v249
	v_cvt_pk_bf16_f32 v243, v250, v251
	s_nop 1
	v_permlane16_swap_b32 v240, v242
	v_permlane16_swap_b32 v241, v243
	global_store_dwordx4 v[144:145], v[240:243], off
	v_max_f32_e32 v248, v24, v24
	v_max_f32_e32 v249, v25, v25
	v_max_f32_e32 v250, v26, v26
	v_max_f32_e32 v251, v27, v27
	v_max_f32_e32 v248, 0, v248
	v_max_f32_e32 v249, 0, v249
	v_max_f32_e32 v250, 0, v250
	v_max_f32_e32 v251, 0, v251
	v_mul_f32_e32 v248, v248, v248
	v_mul_f32_e32 v249, v249, v249
	v_mul_f32_e32 v250, v250, v250
	v_mul_f32_e32 v251, v251, v251
	v_cvt_pk_bf16_f32 v244, v248, v249
	v_cvt_pk_bf16_f32 v245, v250, v251
	v_max_f32_e32 v248, v20, v20
	v_max_f32_e32 v249, v21, v21
	v_max_f32_e32 v250, v22, v22
	v_max_f32_e32 v251, v23, v23
	v_max_f32_e32 v248, 0, v248
	v_max_f32_e32 v249, 0, v249
	v_max_f32_e32 v250, 0, v250
	v_max_f32_e32 v251, 0, v251
	v_mul_f32_e32 v248, v248, v248
	v_mul_f32_e32 v249, v249, v249
	v_mul_f32_e32 v250, v250, v250
	v_mul_f32_e32 v251, v251, v251
	v_cvt_pk_bf16_f32 v246, v248, v249
	v_cvt_pk_bf16_f32 v247, v250, v251
	s_nop 1
	v_permlane16_swap_b32 v244, v246
	v_permlane16_swap_b32 v245, v247
	global_store_dwordx4 v[144:145], v[244:247], off offset:256
	v_lshl_add_u64 v[144:145], s[2:3], 0, v[144:145]
	v_max_f32_e32 v248, v16, v16
	v_max_f32_e32 v249, v17, v17
	v_max_f32_e32 v250, v18, v18
	v_max_f32_e32 v251, v19, v19
	v_max_f32_e32 v248, 0, v248
	v_max_f32_e32 v249, 0, v249
	v_max_f32_e32 v250, 0, v250
	v_max_f32_e32 v251, 0, v251
	v_mul_f32_e32 v248, v248, v248
	v_mul_f32_e32 v249, v249, v249
	v_mul_f32_e32 v250, v250, v250
	v_mul_f32_e32 v251, v251, v251
	v_cvt_pk_bf16_f32 v240, v248, v249
	v_cvt_pk_bf16_f32 v241, v250, v251
	v_max_f32_e32 v248, v12, v12
	v_max_f32_e32 v249, v13, v13
	v_max_f32_e32 v250, v14, v14
	v_max_f32_e32 v251, v15, v15
	v_max_f32_e32 v248, 0, v248
	v_max_f32_e32 v249, 0, v249
	v_max_f32_e32 v250, 0, v250
	v_max_f32_e32 v251, 0, v251
	v_mul_f32_e32 v248, v248, v248
	v_mul_f32_e32 v249, v249, v249
	v_mul_f32_e32 v250, v250, v250
	v_mul_f32_e32 v251, v251, v251
	v_cvt_pk_bf16_f32 v242, v248, v249
	v_cvt_pk_bf16_f32 v243, v250, v251
	s_nop 1
	v_permlane16_swap_b32 v240, v242
	v_permlane16_swap_b32 v241, v243
	global_store_dwordx4 v[144:145], v[240:243], off
	v_max_f32_e32 v248, v8, v8
	v_max_f32_e32 v249, v9, v9
	v_max_f32_e32 v250, v10, v10
	v_max_f32_e32 v251, v11, v11
	v_max_f32_e32 v248, 0, v248
	v_max_f32_e32 v249, 0, v249
	v_max_f32_e32 v250, 0, v250
	v_max_f32_e32 v251, 0, v251
	v_mul_f32_e32 v248, v248, v248
	v_mul_f32_e32 v249, v249, v249
	v_mul_f32_e32 v250, v250, v250
	v_mul_f32_e32 v251, v251, v251
	v_cvt_pk_bf16_f32 v244, v248, v249
	v_cvt_pk_bf16_f32 v245, v250, v251
	v_max_f32_e32 v248, v4, v4
	v_max_f32_e32 v249, v5, v5
	v_max_f32_e32 v250, v6, v6
	v_max_f32_e32 v251, v7, v7
	v_max_f32_e32 v248, 0, v248
	v_max_f32_e32 v249, 0, v249
	v_max_f32_e32 v250, 0, v250
	v_max_f32_e32 v251, 0, v251
	v_mul_f32_e32 v248, v248, v248
	v_mul_f32_e32 v249, v249, v249
	v_mul_f32_e32 v250, v250, v250
	v_mul_f32_e32 v251, v251, v251
	v_cvt_pk_bf16_f32 v246, v248, v249
	v_cvt_pk_bf16_f32 v247, v250, v251
	s_nop 1
	v_permlane16_swap_b32 v244, v246
	v_permlane16_swap_b32 v245, v247
	global_store_dwordx4 v[144:145], v[244:247], off offset:256
	s_branch .LBB0_1310
